# GEMM1 epilogue: separate adjacent u and bg bodies (bg no longer jumps over the gelu blocks), on top of the block layout
# baseline (speedup 1.0000x reference)
; __device__ __forceinline__ float gelu_tanh(float x) { const float u = 1.5957691216f * (x + 0.044715f * x * x * x); return x * __builtin_amdgcn_rcpf(1.f + __expf(-u)); }
; __device__ __forceinline__ void st_bf16x8(bf16_t* p, const f32x4 a, const f32x4 b) { uint4 o; o.x = cvt_pk_bf16(a[0], a[1]); o.y = cvt_pk_bf16(a[2], a[3]); o.z = cvt_pk_bf16(b[0], b[1]); o.w = cvt_pk_bf16(b[2], b[3]); *(uint4*)p = o; }
;     __device__ __forceinline__ void row(const f32x4 (&a)[2][2], int row, int pn, int wc, int fq) const {
;         if (pn < 2 || pn == 4 || pn == 5) {
;             bf16_t* dst = (pn < 2 ? pU : pBG) + (size_t)row * 512 + (pn & 1) * 256 + wc * 32 + 8 * fq;
; #pragma unroll
;             for (int bj = 0; bj < 2; ++bj) { f32x4 v0 = a[bj][0], v1 = a[bj][1];
;                 if (pn < 2) {
; #pragma unroll
;                     for (int j = 0; j < 4; ++j) { v0[j] = gelu_tanh(v0[j]); v1[j] = gelu_tanh(v1[j]); } }
;                 st_bf16x8(dst + bj * HALF, v0, v1); }
.LBB0_246:
	s_and_b64 vcc, exec, s[4:5]
	s_cbranch_vccnz .Lbg_1
	s_branch .Lu_1

; __device__ __forceinline__ float gelu_tanh(float x) { const float u = 1.5957691216f * (x + 0.044715f * x * x * x); return x * __builtin_amdgcn_rcpf(1.f + __expf(-u)); }
; __device__ __forceinline__ void st_bf16x8(bf16_t* p, const f32x4 a, const f32x4 b) { uint4 o; o.x = cvt_pk_bf16(a[0], a[1]); o.y = cvt_pk_bf16(a[2], a[3]); o.z = cvt_pk_bf16(b[0], b[1]); o.w = cvt_pk_bf16(b[2], b[3]); *(uint4*)p = o; }
;     __device__ __forceinline__ void row(const f32x4 (&a)[2][2], int row, int pn, int wc, int fq) const {
;     ...
;             for (int bj = 0; bj < 2; ++bj) { f32x4 v0 = a[bj][0], v1 = a[bj][1];
;                 if (pn < 2) {
; #pragma unroll
;                     for (int j = 0; j < 4; ++j) { v0[j] = gelu_tanh(v0[j]); v1[j] = gelu_tanh(v1[j]); } }
;                 st_bf16x8(dst + bj * HALF, v0, v1); }
.Lu_1:
	v_mov_b32_e32 v190, 0x3d372713
	v_mov_b32_e32 v192, 0xbfcc422a
	v_mov_b32_e32 v194, 0x3fb8aa3b
	v_pk_mul_f32 v[196:197], v[104:105], v[190:191] op_sel_hi:[1,0]
	v_pk_mul_f32 v[198:199], v[106:107], v[190:191] op_sel_hi:[1,0]
	v_pk_mul_f32 v[200:201], v[108:109], v[190:191] op_sel_hi:[1,0]
	v_pk_mul_f32 v[202:203], v[110:111], v[190:191] op_sel_hi:[1,0]
	v_pk_mul_f32 v[196:197], v[104:105], v[196:197]
	v_pk_mul_f32 v[198:199], v[106:107], v[198:199]
	v_pk_mul_f32 v[200:201], v[108:109], v[200:201]
	v_pk_mul_f32 v[202:203], v[110:111], v[202:203]
	v_pk_fma_f32 v[196:197], v[104:105], v[196:197], v[104:105]
	v_pk_fma_f32 v[198:199], v[106:107], v[198:199], v[106:107]
	v_pk_fma_f32 v[200:201], v[108:109], v[200:201], v[108:109]
	v_pk_fma_f32 v[202:203], v[110:111], v[202:203], v[110:111]
	v_pk_mul_f32 v[196:197], v[196:197], v[192:193] op_sel_hi:[1,0]
	v_pk_mul_f32 v[198:199], v[198:199], v[192:193] op_sel_hi:[1,0]
	v_pk_mul_f32 v[200:201], v[200:201], v[192:193] op_sel_hi:[1,0]
	v_pk_mul_f32 v[202:203], v[202:203], v[192:193] op_sel_hi:[1,0]
	v_pk_mul_f32 v[196:197], v[196:197], v[194:195] op_sel_hi:[1,0]
	v_pk_mul_f32 v[198:199], v[198:199], v[194:195] op_sel_hi:[1,0]
	v_pk_mul_f32 v[200:201], v[200:201], v[194:195] op_sel_hi:[1,0]
	v_pk_mul_f32 v[202:203], v[202:203], v[194:195] op_sel_hi:[1,0]
	v_exp_f32_e32 v196, v196
	v_exp_f32_e32 v197, v197
	v_exp_f32_e32 v198, v198
	v_exp_f32_e32 v199, v199
	v_exp_f32_e32 v200, v200
	v_exp_f32_e32 v201, v201
	v_exp_f32_e32 v202, v202
	v_exp_f32_e32 v203, v203
	v_pk_add_f32 v[196:197], v[196:197], 1.0 op_sel_hi:[1,0]
	v_pk_add_f32 v[198:199], v[198:199], 1.0 op_sel_hi:[1,0]
	v_pk_add_f32 v[200:201], v[200:201], 1.0 op_sel_hi:[1,0]
	v_pk_add_f32 v[202:203], v[202:203], 1.0 op_sel_hi:[1,0]
	v_rcp_f32_e32 v196, v196
	v_rcp_f32_e32 v197, v197
	v_rcp_f32_e32 v198, v198
	v_rcp_f32_e32 v199, v199
	v_rcp_f32_e32 v200, v200
	v_rcp_f32_e32 v201, v201
	v_rcp_f32_e32 v202, v202
	v_rcp_f32_e32 v203, v203
	v_pk_mul_f32 v[104:105], v[104:105], v[196:197]
	v_pk_mul_f32 v[106:107], v[106:107], v[198:199]
	v_pk_mul_f32 v[108:109], v[108:109], v[200:201]
	v_pk_mul_f32 v[110:111], v[110:111], v[202:203]
	s_nop 0
	s_nop 0
	s_nop 0
	s_nop 0

; __device__ __forceinline__ float gelu_tanh(float x) { const float u = 1.5957691216f * (x + 0.044715f * x * x * x); return x * __builtin_amdgcn_rcpf(1.f + __expf(-u)); }
; __device__ __forceinline__ void st_bf16x8(bf16_t* p, const f32x4 a, const f32x4 b) { uint4 o; o.x = cvt_pk_bf16(a[0], a[1]); o.y = cvt_pk_bf16(a[2], a[3]); o.z = cvt_pk_bf16(b[0], b[1]); o.w = cvt_pk_bf16(b[2], b[3]); *(uint4*)p = o; }
;     __device__ __forceinline__ void row(const f32x4 (&a)[2][2], int row, int pn, int wc, int fq) const {
;     ...
;             for (int bj = 0; bj < 2; ++bj) { f32x4 v0 = a[bj][0], v1 = a[bj][1];
;                 if (pn < 2) {
; #pragma unroll
;                     for (int j = 0; j < 4; ++j) { v0[j] = gelu_tanh(v0[j]); v1[j] = gelu_tanh(v1[j]); } }
;                 st_bf16x8(dst + bj * HALF, v0, v1); }
.Lu_2:
	v_mov_b32_e32 v190, 0x3d372713
	v_mov_b32_e32 v192, 0xbfcc422a
	v_mov_b32_e32 v194, 0x3fb8aa3b
	v_pk_mul_f32 v[196:197], v[88:89], v[190:191] op_sel_hi:[1,0]
	v_pk_mul_f32 v[198:199], v[90:91], v[190:191] op_sel_hi:[1,0]
	v_pk_mul_f32 v[200:201], v[92:93], v[190:191] op_sel_hi:[1,0]
	v_pk_mul_f32 v[202:203], v[94:95], v[190:191] op_sel_hi:[1,0]
	v_pk_mul_f32 v[196:197], v[88:89], v[196:197]
	v_pk_mul_f32 v[198:199], v[90:91], v[198:199]
	v_pk_mul_f32 v[200:201], v[92:93], v[200:201]
	v_pk_mul_f32 v[202:203], v[94:95], v[202:203]
	v_pk_fma_f32 v[196:197], v[88:89], v[196:197], v[88:89]
	v_pk_fma_f32 v[198:199], v[90:91], v[198:199], v[90:91]
	v_pk_fma_f32 v[200:201], v[92:93], v[200:201], v[92:93]
	v_pk_fma_f32 v[202:203], v[94:95], v[202:203], v[94:95]
	v_pk_mul_f32 v[196:197], v[196:197], v[192:193] op_sel_hi:[1,0]
	v_pk_mul_f32 v[198:199], v[198:199], v[192:193] op_sel_hi:[1,0]
	v_pk_mul_f32 v[200:201], v[200:201], v[192:193] op_sel_hi:[1,0]
	v_pk_mul_f32 v[202:203], v[202:203], v[192:193] op_sel_hi:[1,0]
	v_pk_mul_f32 v[196:197], v[196:197], v[194:195] op_sel_hi:[1,0]
	v_pk_mul_f32 v[198:199], v[198:199], v[194:195] op_sel_hi:[1,0]
	v_pk_mul_f32 v[200:201], v[200:201], v[194:195] op_sel_hi:[1,0]
	v_pk_mul_f32 v[202:203], v[202:203], v[194:195] op_sel_hi:[1,0]
	v_exp_f32_e32 v196, v196
	v_exp_f32_e32 v197, v197
	v_exp_f32_e32 v198, v198
	v_exp_f32_e32 v199, v199
	v_exp_f32_e32 v200, v200
	v_exp_f32_e32 v201, v201
	v_exp_f32_e32 v202, v202
	v_exp_f32_e32 v203, v203
	v_pk_add_f32 v[196:197], v[196:197], 1.0 op_sel_hi:[1,0]
	v_pk_add_f32 v[198:199], v[198:199], 1.0 op_sel_hi:[1,0]
	v_pk_add_f32 v[200:201], v[200:201], 1.0 op_sel_hi:[1,0]
	v_pk_add_f32 v[202:203], v[202:203], 1.0 op_sel_hi:[1,0]
	v_rcp_f32_e32 v196, v196
	v_rcp_f32_e32 v197, v197
	v_rcp_f32_e32 v198, v198
	v_rcp_f32_e32 v199, v199
	v_rcp_f32_e32 v200, v200
	v_rcp_f32_e32 v201, v201
	v_rcp_f32_e32 v202, v202
	v_rcp_f32_e32 v203, v203
	v_pk_mul_f32 v[88:89], v[88:89], v[196:197]
	v_pk_mul_f32 v[90:91], v[90:91], v[198:199]
	v_pk_mul_f32 v[92:93], v[92:93], v[200:201]
	v_pk_mul_f32 v[94:95], v[94:95], v[202:203]
	s_nop 0
	s_nop 0
	s_nop 0
	s_nop 0

; __device__ __forceinline__ float gelu_tanh(float x) { const float u = 1.5957691216f * (x + 0.044715f * x * x * x); return x * __builtin_amdgcn_rcpf(1.f + __expf(-u)); }
; __device__ __forceinline__ void st_bf16x8(bf16_t* p, const f32x4 a, const f32x4 b) { uint4 o; o.x = cvt_pk_bf16(a[0], a[1]); o.y = cvt_pk_bf16(a[2], a[3]); o.z = cvt_pk_bf16(b[0], b[1]); o.w = cvt_pk_bf16(b[2], b[3]); *(uint4*)p = o; }
;     __device__ __forceinline__ void row(const f32x4 (&a)[2][2], int row, int pn, int wc, int fq) const {
;     ...
;             for (int bj = 0; bj < 2; ++bj) { f32x4 v0 = a[bj][0], v1 = a[bj][1];
;                 if (pn < 2) {
; #pragma unroll
;                     for (int j = 0; j < 4; ++j) { v0[j] = gelu_tanh(v0[j]); v1[j] = gelu_tanh(v1[j]); } }
;                 st_bf16x8(dst + bj * HALF, v0, v1); }
.Lu_3:
	v_mov_b32_e32 v190, 0x3d372713
	v_mov_b32_e32 v192, 0xbfcc422a
	v_mov_b32_e32 v194, 0x3fb8aa3b
	v_pk_mul_f32 v[196:197], v[72:73], v[190:191] op_sel_hi:[1,0]
	v_pk_mul_f32 v[198:199], v[74:75], v[190:191] op_sel_hi:[1,0]
	v_pk_mul_f32 v[200:201], v[76:77], v[190:191] op_sel_hi:[1,0]
	v_pk_mul_f32 v[202:203], v[78:79], v[190:191] op_sel_hi:[1,0]
	v_pk_mul_f32 v[196:197], v[72:73], v[196:197]
	v_pk_mul_f32 v[198:199], v[74:75], v[198:199]
	v_pk_mul_f32 v[200:201], v[76:77], v[200:201]
	v_pk_mul_f32 v[202:203], v[78:79], v[202:203]
	v_pk_fma_f32 v[196:197], v[72:73], v[196:197], v[72:73]
	v_pk_fma_f32 v[198:199], v[74:75], v[198:199], v[74:75]
	v_pk_fma_f32 v[200:201], v[76:77], v[200:201], v[76:77]
	v_pk_fma_f32 v[202:203], v[78:79], v[202:203], v[78:79]
	v_pk_mul_f32 v[196:197], v[196:197], v[192:193] op_sel_hi:[1,0]
	v_pk_mul_f32 v[198:199], v[198:199], v[192:193] op_sel_hi:[1,0]
	v_pk_mul_f32 v[200:201], v[200:201], v[192:193] op_sel_hi:[1,0]
	v_pk_mul_f32 v[202:203], v[202:203], v[192:193] op_sel_hi:[1,0]
	v_pk_mul_f32 v[196:197], v[196:197], v[194:195] op_sel_hi:[1,0]
	v_pk_mul_f32 v[198:199], v[198:199], v[194:195] op_sel_hi:[1,0]
	v_pk_mul_f32 v[200:201], v[200:201], v[194:195] op_sel_hi:[1,0]
	v_pk_mul_f32 v[202:203], v[202:203], v[194:195] op_sel_hi:[1,0]
	v_exp_f32_e32 v196, v196
	v_exp_f32_e32 v197, v197
	v_exp_f32_e32 v198, v198
	v_exp_f32_e32 v199, v199
	v_exp_f32_e32 v200, v200
	v_exp_f32_e32 v201, v201
	v_exp_f32_e32 v202, v202
	v_exp_f32_e32 v203, v203
	v_pk_add_f32 v[196:197], v[196:197], 1.0 op_sel_hi:[1,0]
	v_pk_add_f32 v[198:199], v[198:199], 1.0 op_sel_hi:[1,0]
	v_pk_add_f32 v[200:201], v[200:201], 1.0 op_sel_hi:[1,0]
	v_pk_add_f32 v[202:203], v[202:203], 1.0 op_sel_hi:[1,0]
	v_rcp_f32_e32 v196, v196
	v_rcp_f32_e32 v197, v197
	v_rcp_f32_e32 v198, v198
	v_rcp_f32_e32 v199, v199
	v_rcp_f32_e32 v200, v200
	v_rcp_f32_e32 v201, v201
	v_rcp_f32_e32 v202, v202
	v_rcp_f32_e32 v203, v203
	v_pk_mul_f32 v[72:73], v[72:73], v[196:197]
	v_pk_mul_f32 v[74:75], v[74:75], v[198:199]
	v_pk_mul_f32 v[76:77], v[76:77], v[200:201]
	v_pk_mul_f32 v[78:79], v[78:79], v[202:203]
	s_nop 0
	s_nop 0
	s_nop 0
	s_nop 0

; __device__ __forceinline__ float gelu_tanh(float x) { const float u = 1.5957691216f * (x + 0.044715f * x * x * x); return x * __builtin_amdgcn_rcpf(1.f + __expf(-u)); }
; __device__ __forceinline__ void st_bf16x8(bf16_t* p, const f32x4 a, const f32x4 b) { uint4 o; o.x = cvt_pk_bf16(a[0], a[1]); o.y = cvt_pk_bf16(a[2], a[3]); o.z = cvt_pk_bf16(b[0], b[1]); o.w = cvt_pk_bf16(b[2], b[3]); *(uint4*)p = o; }
;     __device__ __forceinline__ void row(const f32x4 (&a)[2][2], int row, int pn, int wc, int fq) const {
;         if (pn < 2 || pn == 4 || pn == 5) {
;             bf16_t* dst = (pn < 2 ? pU : pBG) + (size_t)row * 512 + (pn & 1) * 256 + wc * 32 + 8 * fq;
; #pragma unroll
;             for (int bj = 0; bj < 2; ++bj) { f32x4 v0 = a[bj][0], v1 = a[bj][1];
;                 if (pn < 2) {
; #pragma unroll
;                     for (int j = 0; j < 4; ++j) { v0[j] = gelu_tanh(v0[j]); v1[j] = gelu_tanh(v1[j]); } }
;                 st_bf16x8(dst + bj * HALF, v0, v1); }
.LBB0_282:
	v_cvt_pk_bf16_f32 v68, v68, v69
	v_cvt_pk_bf16_f32 v69, v70, v71
	v_cvt_pk_bf16_f32 v70, v64, v65
	s_nop 0
	v_cvt_pk_bf16_f32 v71, v66, v67
	global_store_dwordx4 v[80:81], v[68:71], off offset:256
	s_branch .LBB0_283
.Lbg_1:
	s_and_b64 s[0:1], s[80:81], exec
	v_ashrrev_i32_e32 v121, 31, v120
	s_cselect_b32 s1, s31, s49
	s_cselect_b32 s0, s30, s48
	v_lshlrev_b64 v[112:113], 10, v[120:121]
	v_lshl_add_u64 v[112:113], s[0:1], 0, v[112:113]
	s_lshl_b32 s64, s61, 1
	v_lshl_add_u64 v[112:113], v[112:113], 0, s[64:65]
	s_lshl_b32 s64, s91, 1
	v_lshl_add_u64 v[112:113], v[112:113], 0, s[64:65]
	v_lshlrev_b32_e32 v114, 1, v142
	v_mov_b32_e32 v115, v141
	v_lshl_add_u64 v[112:113], v[112:113], 0, v[114:115]
	s_and_b64 vcc, exec, s[4:5]
	v_cvt_pk_bf16_f32 v108, v108, v109
	v_cvt_pk_bf16_f32 v109, v110, v111
	v_cvt_pk_bf16_f32 v110, v104, v105
	v_cvt_pk_bf16_f32 v111, v106, v107
	global_store_dwordx4 v[112:113], v[108:111], off
	v_cvt_pk_bf16_f32 v100, v100, v101
	v_cvt_pk_bf16_f32 v101, v102, v103
	v_cvt_pk_bf16_f32 v102, v96, v97
	s_nop 0
	v_cvt_pk_bf16_f32 v103, v98, v99
	global_store_dwordx4 v[112:113], v[100:103], off offset:256
	v_or_b32_e32 v104, 32, v156
	s_and_b64 vcc, exec, s[8:9]
	s_mov_b64 s[0:1], -1
	s_cbranch_vccnz .LBB0_233
	s_branch .LBB0_251
.Lbg_2:
	s_and_b64 s[0:1], s[80:81], exec
	v_ashrrev_i32_e32 v105, 31, v104
	s_cselect_b32 s1, s31, s49
	s_cselect_b32 s0, s30, s48
	v_lshlrev_b64 v[96:97], 10, v[104:105]
	v_lshl_add_u64 v[96:97], s[0:1], 0, v[96:97]
	s_lshl_b32 s64, s61, 1
	v_lshl_add_u64 v[96:97], v[96:97], 0, s[64:65]
	s_lshl_b32 s64, s91, 1
	v_lshl_add_u64 v[96:97], v[96:97], 0, s[64:65]
	v_lshlrev_b32_e32 v98, 1, v142
	v_mov_b32_e32 v99, v141
	v_lshl_add_u64 v[96:97], v[96:97], 0, v[98:99]
	s_and_b64 vcc, exec, s[4:5]
	v_cvt_pk_bf16_f32 v92, v92, v93
	v_cvt_pk_bf16_f32 v93, v94, v95
	v_cvt_pk_bf16_f32 v94, v88, v89
	v_cvt_pk_bf16_f32 v95, v90, v91
	global_store_dwordx4 v[96:97], v[92:95], off
	v_cvt_pk_bf16_f32 v84, v84, v85
	v_cvt_pk_bf16_f32 v85, v86, v87
	v_cvt_pk_bf16_f32 v86, v80, v81
	s_nop 0
	v_cvt_pk_bf16_f32 v87, v82, v83
	global_store_dwordx4 v[96:97], v[84:87], off offset:256
	v_or_b32_e32 v88, 48, v156
	s_and_b64 vcc, exec, s[8:9]
	s_mov_b64 s[0:1], -1
	s_cbranch_vccnz .LBB0_235
	s_branch .LBB0_266
.Lbg_3:
	s_and_b64 s[0:1], s[80:81], exec
	v_ashrrev_i32_e32 v89, 31, v88
	s_cselect_b32 s1, s31, s49
	s_cselect_b32 s0, s30, s48
	v_lshlrev_b64 v[80:81], 10, v[88:89]
	v_lshl_add_u64 v[80:81], s[0:1], 0, v[80:81]
	s_lshl_b32 s64, s61, 1
	v_lshl_add_u64 v[80:81], v[80:81], 0, s[64:65]
	s_lshl_b32 s64, s91, 1
	v_lshl_add_u64 v[80:81], v[80:81], 0, s[64:65]
	v_lshlrev_b32_e32 v82, 1, v142
	v_mov_b32_e32 v83, v141
	v_lshl_add_u64 v[80:81], v[80:81], 0, v[82:83]
	s_and_b64 vcc, exec, s[4:5]
	v_cvt_pk_bf16_f32 v76, v76, v77
	v_cvt_pk_bf16_f32 v77, v78, v79
	v_cvt_pk_bf16_f32 v78, v72, v73
	v_cvt_pk_bf16_f32 v79, v74, v75
	global_store_dwordx4 v[80:81], v[76:79], off
	v_cvt_pk_bf16_f32 v68, v68, v69
	v_cvt_pk_bf16_f32 v69, v70, v71
	v_cvt_pk_bf16_f32 v70, v64, v65
	s_nop 0
	v_cvt_pk_bf16_f32 v71, v66, v67
	global_store_dwordx4 v[80:81], v[68:71], off offset:256
	s_branch .LBB0_283

; __device__ __forceinline__ float gelu_tanh(float x) { const float u = 1.5957691216f * (x + 0.044715f * x * x * x); return x * __builtin_amdgcn_rcpf(1.f + __expf(-u)); }
; __device__ __forceinline__ void st_bf16x8(bf16_t* p, const f32x4 a, const f32x4 b) { uint4 o; o.x = cvt_pk_bf16(a[0], a[1]); o.y = cvt_pk_bf16(a[2], a[3]); o.z = cvt_pk_bf16(b[0], b[1]); o.w = cvt_pk_bf16(b[2], b[3]); *(uint4*)p = o; }
;     __device__ __forceinline__ void row(const f32x4 (&a)[2][2], int row, int pn, int wc, int fq) const {
;     ...
;             for (int bj = 0; bj < 2; ++bj) { f32x4 v0 = a[bj][0], v1 = a[bj][1];
;                 if (pn < 2) {
; #pragma unroll
;                     for (int j = 0; j < 4; ++j) { v0[j] = gelu_tanh(v0[j]); v1[j] = gelu_tanh(v1[j]); } }
;                 st_bf16x8(dst + bj * HALF, v0, v1); }
.Lu_4:
	v_mov_b32_e32 v190, 0x3d372713
	v_mov_b32_e32 v192, 0xbfcc422a
	v_mov_b32_e32 v194, 0x3fb8aa3b
	v_pk_mul_f32 v[196:197], v[56:57], v[190:191] op_sel_hi:[1,0]
	v_pk_mul_f32 v[198:199], v[58:59], v[190:191] op_sel_hi:[1,0]
	v_pk_mul_f32 v[200:201], v[60:61], v[190:191] op_sel_hi:[1,0]
	v_pk_mul_f32 v[202:203], v[62:63], v[190:191] op_sel_hi:[1,0]
	v_pk_mul_f32 v[196:197], v[56:57], v[196:197]
	v_pk_mul_f32 v[198:199], v[58:59], v[198:199]
	v_pk_mul_f32 v[200:201], v[60:61], v[200:201]
	v_pk_mul_f32 v[202:203], v[62:63], v[202:203]
	v_pk_fma_f32 v[196:197], v[56:57], v[196:197], v[56:57]
	v_pk_fma_f32 v[198:199], v[58:59], v[198:199], v[58:59]
	v_pk_fma_f32 v[200:201], v[60:61], v[200:201], v[60:61]
	v_pk_fma_f32 v[202:203], v[62:63], v[202:203], v[62:63]
	v_pk_mul_f32 v[196:197], v[196:197], v[192:193] op_sel_hi:[1,0]
	v_pk_mul_f32 v[198:199], v[198:199], v[192:193] op_sel_hi:[1,0]
	v_pk_mul_f32 v[200:201], v[200:201], v[192:193] op_sel_hi:[1,0]
	v_pk_mul_f32 v[202:203], v[202:203], v[192:193] op_sel_hi:[1,0]
	v_pk_mul_f32 v[196:197], v[196:197], v[194:195] op_sel_hi:[1,0]
	v_pk_mul_f32 v[198:199], v[198:199], v[194:195] op_sel_hi:[1,0]
	v_pk_mul_f32 v[200:201], v[200:201], v[194:195] op_sel_hi:[1,0]
	v_pk_mul_f32 v[202:203], v[202:203], v[194:195] op_sel_hi:[1,0]
	v_exp_f32_e32 v196, v196
	v_exp_f32_e32 v197, v197
	v_exp_f32_e32 v198, v198
	v_exp_f32_e32 v199, v199
	v_exp_f32_e32 v200, v200
	v_exp_f32_e32 v201, v201
	v_exp_f32_e32 v202, v202
	v_exp_f32_e32 v203, v203
	v_pk_add_f32 v[196:197], v[196:197], 1.0 op_sel_hi:[1,0]
	v_pk_add_f32 v[198:199], v[198:199], 1.0 op_sel_hi:[1,0]
	v_pk_add_f32 v[200:201], v[200:201], 1.0 op_sel_hi:[1,0]
	v_pk_add_f32 v[202:203], v[202:203], 1.0 op_sel_hi:[1,0]
	v_rcp_f32_e32 v196, v196
	v_rcp_f32_e32 v197, v197
	v_rcp_f32_e32 v198, v198
	v_rcp_f32_e32 v199, v199
	v_rcp_f32_e32 v200, v200
	v_rcp_f32_e32 v201, v201
	v_rcp_f32_e32 v202, v202
	v_rcp_f32_e32 v203, v203
	v_pk_mul_f32 v[56:57], v[56:57], v[196:197]
	v_pk_mul_f32 v[58:59], v[58:59], v[198:199]
	v_pk_mul_f32 v[60:61], v[60:61], v[200:201]
	v_pk_mul_f32 v[62:63], v[62:63], v[202:203]
	s_nop 0
	s_nop 0
	s_nop 0
	s_nop 0

; __device__ __forceinline__ float gelu_tanh(float x) { const float u = 1.5957691216f * (x + 0.044715f * x * x * x); return x * __builtin_amdgcn_rcpf(1.f + __expf(-u)); }
; __device__ __forceinline__ void st_bf16x8(bf16_t* p, const f32x4 a, const f32x4 b) { uint4 o; o.x = cvt_pk_bf16(a[0], a[1]); o.y = cvt_pk_bf16(a[2], a[3]); o.z = cvt_pk_bf16(b[0], b[1]); o.w = cvt_pk_bf16(b[2], b[3]); *(uint4*)p = o; }
;     __device__ __forceinline__ void row(const f32x4 (&a)[2][2], int row, int pn, int wc, int fq) const {
;     ...
;             for (int bj = 0; bj < 2; ++bj) { f32x4 v0 = a[bj][0], v1 = a[bj][1];
;                 if (pn < 2) {
; #pragma unroll
;                     for (int j = 0; j < 4; ++j) { v0[j] = gelu_tanh(v0[j]); v1[j] = gelu_tanh(v1[j]); } }
;                 st_bf16x8(dst + bj * HALF, v0, v1); }
.Lu_5:
	v_mov_b32_e32 v190, 0x3d372713
	v_mov_b32_e32 v192, 0xbfcc422a
	v_mov_b32_e32 v194, 0x3fb8aa3b
	v_pk_mul_f32 v[196:197], v[40:41], v[190:191] op_sel_hi:[1,0]
	v_pk_mul_f32 v[198:199], v[42:43], v[190:191] op_sel_hi:[1,0]
	v_pk_mul_f32 v[200:201], v[44:45], v[190:191] op_sel_hi:[1,0]
	v_pk_mul_f32 v[202:203], v[46:47], v[190:191] op_sel_hi:[1,0]
	v_pk_mul_f32 v[196:197], v[40:41], v[196:197]
	v_pk_mul_f32 v[198:199], v[42:43], v[198:199]
	v_pk_mul_f32 v[200:201], v[44:45], v[200:201]
	v_pk_mul_f32 v[202:203], v[46:47], v[202:203]
	v_pk_fma_f32 v[196:197], v[40:41], v[196:197], v[40:41]
	v_pk_fma_f32 v[198:199], v[42:43], v[198:199], v[42:43]
	v_pk_fma_f32 v[200:201], v[44:45], v[200:201], v[44:45]
	v_pk_fma_f32 v[202:203], v[46:47], v[202:203], v[46:47]
	v_pk_mul_f32 v[196:197], v[196:197], v[192:193] op_sel_hi:[1,0]
	v_pk_mul_f32 v[198:199], v[198:199], v[192:193] op_sel_hi:[1,0]
	v_pk_mul_f32 v[200:201], v[200:201], v[192:193] op_sel_hi:[1,0]
	v_pk_mul_f32 v[202:203], v[202:203], v[192:193] op_sel_hi:[1,0]
	v_pk_mul_f32 v[196:197], v[196:197], v[194:195] op_sel_hi:[1,0]
	v_pk_mul_f32 v[198:199], v[198:199], v[194:195] op_sel_hi:[1,0]
	v_pk_mul_f32 v[200:201], v[200:201], v[194:195] op_sel_hi:[1,0]
	v_pk_mul_f32 v[202:203], v[202:203], v[194:195] op_sel_hi:[1,0]
	v_exp_f32_e32 v196, v196
	v_exp_f32_e32 v197, v197
	v_exp_f32_e32 v198, v198
	v_exp_f32_e32 v199, v199
	v_exp_f32_e32 v200, v200
	v_exp_f32_e32 v201, v201
	v_exp_f32_e32 v202, v202
	v_exp_f32_e32 v203, v203
	v_pk_add_f32 v[196:197], v[196:197], 1.0 op_sel_hi:[1,0]
	v_pk_add_f32 v[198:199], v[198:199], 1.0 op_sel_hi:[1,0]
	v_pk_add_f32 v[200:201], v[200:201], 1.0 op_sel_hi:[1,0]
	v_pk_add_f32 v[202:203], v[202:203], 1.0 op_sel_hi:[1,0]
	v_rcp_f32_e32 v196, v196
	v_rcp_f32_e32 v197, v197
	v_rcp_f32_e32 v198, v198
	v_rcp_f32_e32 v199, v199
	v_rcp_f32_e32 v200, v200
	v_rcp_f32_e32 v201, v201
	v_rcp_f32_e32 v202, v202
	v_rcp_f32_e32 v203, v203
	v_pk_mul_f32 v[40:41], v[40:41], v[196:197]
	v_pk_mul_f32 v[42:43], v[42:43], v[198:199]
	v_pk_mul_f32 v[44:45], v[44:45], v[200:201]
	v_pk_mul_f32 v[46:47], v[46:47], v[202:203]
	s_nop 0
	s_nop 0
	s_nop 0
	s_nop 0

; __device__ __forceinline__ float gelu_tanh(float x) { const float u = 1.5957691216f * (x + 0.044715f * x * x * x); return x * __builtin_amdgcn_rcpf(1.f + __expf(-u)); }
; __device__ __forceinline__ void st_bf16x8(bf16_t* p, const f32x4 a, const f32x4 b) { uint4 o; o.x = cvt_pk_bf16(a[0], a[1]); o.y = cvt_pk_bf16(a[2], a[3]); o.z = cvt_pk_bf16(b[0], b[1]); o.w = cvt_pk_bf16(b[2], b[3]); *(uint4*)p = o; }
;     __device__ __forceinline__ void row(const f32x4 (&a)[2][2], int row, int pn, int wc, int fq) const {
;     ...
;             for (int bj = 0; bj < 2; ++bj) { f32x4 v0 = a[bj][0], v1 = a[bj][1];
;                 if (pn < 2) {
; #pragma unroll
;                     for (int j = 0; j < 4; ++j) { v0[j] = gelu_tanh(v0[j]); v1[j] = gelu_tanh(v1[j]); } }
;                 st_bf16x8(dst + bj * HALF, v0, v1); }
.Lu_6:
	v_mov_b32_e32 v190, 0x3d372713
	v_mov_b32_e32 v192, 0xbfcc422a
	v_mov_b32_e32 v194, 0x3fb8aa3b
	v_pk_mul_f32 v[196:197], v[24:25], v[190:191] op_sel_hi:[1,0]
	v_pk_mul_f32 v[198:199], v[26:27], v[190:191] op_sel_hi:[1,0]
	v_pk_mul_f32 v[200:201], v[28:29], v[190:191] op_sel_hi:[1,0]
	v_pk_mul_f32 v[202:203], v[30:31], v[190:191] op_sel_hi:[1,0]
	v_pk_mul_f32 v[196:197], v[24:25], v[196:197]
	v_pk_mul_f32 v[198:199], v[26:27], v[198:199]
	v_pk_mul_f32 v[200:201], v[28:29], v[200:201]
	v_pk_mul_f32 v[202:203], v[30:31], v[202:203]
	v_pk_fma_f32 v[196:197], v[24:25], v[196:197], v[24:25]
	v_pk_fma_f32 v[198:199], v[26:27], v[198:199], v[26:27]
	v_pk_fma_f32 v[200:201], v[28:29], v[200:201], v[28:29]
	v_pk_fma_f32 v[202:203], v[30:31], v[202:203], v[30:31]
	v_pk_mul_f32 v[196:197], v[196:197], v[192:193] op_sel_hi:[1,0]
	v_pk_mul_f32 v[198:199], v[198:199], v[192:193] op_sel_hi:[1,0]
	v_pk_mul_f32 v[200:201], v[200:201], v[192:193] op_sel_hi:[1,0]
	v_pk_mul_f32 v[202:203], v[202:203], v[192:193] op_sel_hi:[1,0]
	v_pk_mul_f32 v[196:197], v[196:197], v[194:195] op_sel_hi:[1,0]
	v_pk_mul_f32 v[198:199], v[198:199], v[194:195] op_sel_hi:[1,0]
	v_pk_mul_f32 v[200:201], v[200:201], v[194:195] op_sel_hi:[1,0]
	v_pk_mul_f32 v[202:203], v[202:203], v[194:195] op_sel_hi:[1,0]
	v_exp_f32_e32 v196, v196
	v_exp_f32_e32 v197, v197
	v_exp_f32_e32 v198, v198
	v_exp_f32_e32 v199, v199
	v_exp_f32_e32 v200, v200
	v_exp_f32_e32 v201, v201
	v_exp_f32_e32 v202, v202
	v_exp_f32_e32 v203, v203
	v_pk_add_f32 v[196:197], v[196:197], 1.0 op_sel_hi:[1,0]
	v_pk_add_f32 v[198:199], v[198:199], 1.0 op_sel_hi:[1,0]
	v_pk_add_f32 v[200:201], v[200:201], 1.0 op_sel_hi:[1,0]
	v_pk_add_f32 v[202:203], v[202:203], 1.0 op_sel_hi:[1,0]
	v_rcp_f32_e32 v196, v196
	v_rcp_f32_e32 v197, v197
	v_rcp_f32_e32 v198, v198
	v_rcp_f32_e32 v199, v199
	v_rcp_f32_e32 v200, v200
	v_rcp_f32_e32 v201, v201
	v_rcp_f32_e32 v202, v202
	v_rcp_f32_e32 v203, v203
	v_pk_mul_f32 v[24:25], v[24:25], v[196:197]
	v_pk_mul_f32 v[26:27], v[26:27], v[198:199]
	v_pk_mul_f32 v[28:29], v[28:29], v[200:201]
	v_pk_mul_f32 v[30:31], v[30:31], v[202:203]
	s_nop 0
	s_nop 0
	s_nop 0
	s_nop 0

; __device__ __forceinline__ float gelu_tanh(float x) { const float u = 1.5957691216f * (x + 0.044715f * x * x * x); return x * __builtin_amdgcn_rcpf(1.f + __expf(-u)); }
; __device__ __forceinline__ void st_bf16x8(bf16_t* p, const f32x4 a, const f32x4 b) { uint4 o; o.x = cvt_pk_bf16(a[0], a[1]); o.y = cvt_pk_bf16(a[2], a[3]); o.z = cvt_pk_bf16(b[0], b[1]); o.w = cvt_pk_bf16(b[2], b[3]); *(uint4*)p = o; }
;     __device__ __forceinline__ void row(const f32x4 (&a)[2][2], int row, int pn, int wc, int fq) const {
;     ...
;             for (int bj = 0; bj < 2; ++bj) { f32x4 v0 = a[bj][0], v1 = a[bj][1];
;                 if (pn < 2) {
; #pragma unroll
;                     for (int j = 0; j < 4; ++j) { v0[j] = gelu_tanh(v0[j]); v1[j] = gelu_tanh(v1[j]); } }
;                 st_bf16x8(dst + bj * HALF, v0, v1); }
.Lu_7:
	v_mov_b32_e32 v190, 0x3d372713
	v_mov_b32_e32 v192, 0xbfcc422a
	v_mov_b32_e32 v194, 0x3fb8aa3b
	v_pk_mul_f32 v[196:197], v[8:9], v[190:191] op_sel_hi:[1,0]
	v_pk_mul_f32 v[198:199], v[10:11], v[190:191] op_sel_hi:[1,0]
	v_pk_mul_f32 v[200:201], v[12:13], v[190:191] op_sel_hi:[1,0]
	v_pk_mul_f32 v[202:203], v[14:15], v[190:191] op_sel_hi:[1,0]
	v_pk_mul_f32 v[196:197], v[8:9], v[196:197]
	v_pk_mul_f32 v[198:199], v[10:11], v[198:199]
	v_pk_mul_f32 v[200:201], v[12:13], v[200:201]
	v_pk_mul_f32 v[202:203], v[14:15], v[202:203]
	v_pk_fma_f32 v[196:197], v[8:9], v[196:197], v[8:9]
	v_pk_fma_f32 v[198:199], v[10:11], v[198:199], v[10:11]
	v_pk_fma_f32 v[200:201], v[12:13], v[200:201], v[12:13]
	v_pk_fma_f32 v[202:203], v[14:15], v[202:203], v[14:15]
	v_pk_mul_f32 v[196:197], v[196:197], v[192:193] op_sel_hi:[1,0]
	v_pk_mul_f32 v[198:199], v[198:199], v[192:193] op_sel_hi:[1,0]
	v_pk_mul_f32 v[200:201], v[200:201], v[192:193] op_sel_hi:[1,0]
	v_pk_mul_f32 v[202:203], v[202:203], v[192:193] op_sel_hi:[1,0]
	v_pk_mul_f32 v[196:197], v[196:197], v[194:195] op_sel_hi:[1,0]
	v_pk_mul_f32 v[198:199], v[198:199], v[194:195] op_sel_hi:[1,0]
	v_pk_mul_f32 v[200:201], v[200:201], v[194:195] op_sel_hi:[1,0]
	v_pk_mul_f32 v[202:203], v[202:203], v[194:195] op_sel_hi:[1,0]
	v_exp_f32_e32 v196, v196
	v_exp_f32_e32 v197, v197
	v_exp_f32_e32 v198, v198
	v_exp_f32_e32 v199, v199
	v_exp_f32_e32 v200, v200
	v_exp_f32_e32 v201, v201
	v_exp_f32_e32 v202, v202
	v_exp_f32_e32 v203, v203
	v_pk_add_f32 v[196:197], v[196:197], 1.0 op_sel_hi:[1,0]
	v_pk_add_f32 v[198:199], v[198:199], 1.0 op_sel_hi:[1,0]
	v_pk_add_f32 v[200:201], v[200:201], 1.0 op_sel_hi:[1,0]
	v_pk_add_f32 v[202:203], v[202:203], 1.0 op_sel_hi:[1,0]
	v_rcp_f32_e32 v196, v196
	v_rcp_f32_e32 v197, v197
	v_rcp_f32_e32 v198, v198
	v_rcp_f32_e32 v199, v199
	v_rcp_f32_e32 v200, v200
	v_rcp_f32_e32 v201, v201
	v_rcp_f32_e32 v202, v202
	v_rcp_f32_e32 v203, v203
	v_pk_mul_f32 v[8:9], v[8:9], v[196:197]
	v_pk_mul_f32 v[10:11], v[10:11], v[198:199]
	v_pk_mul_f32 v[12:13], v[12:13], v[200:201]
	v_pk_mul_f32 v[14:15], v[14:15], v[202:203]

; __device__ __forceinline__ float gelu_tanh(float x) { const float u = 1.5957691216f * (x + 0.044715f * x * x * x); return x * __builtin_amdgcn_rcpf(1.f + __expf(-u)); }
; __device__ __forceinline__ void st_bf16x8(bf16_t* p, const f32x4 a, const f32x4 b) { uint4 o; o.x = cvt_pk_bf16(a[0], a[1]); o.y = cvt_pk_bf16(a[2], a[3]); o.z = cvt_pk_bf16(b[0], b[1]); o.w = cvt_pk_bf16(b[2], b[3]); *(uint4*)p = o; }
;     __device__ __forceinline__ void row(const f32x4 (&a)[2][2], int row, int pn, int wc, int fq) const {
;         if (pn < 2 || pn == 4 || pn == 5) {
;             bf16_t* dst = (pn < 2 ? pU : pBG) + (size_t)row * 512 + (pn & 1) * 256 + wc * 32 + 8 * fq;
; #pragma unroll
;             for (int bj = 0; bj < 2; ++bj) { f32x4 v0 = a[bj][0], v1 = a[bj][1];
;                 if (pn < 2) {
; #pragma unroll
;                     for (int j = 0; j < 4; ++j) { v0[j] = gelu_tanh(v0[j]); v1[j] = gelu_tanh(v1[j]); } }
;                 st_bf16x8(dst + bj * HALF, v0, v1); }
.Lbg_4:
	s_and_b64 s[0:1], s[80:81], exec
	v_ashrrev_i32_e32 v73, 31, v72
	s_cselect_b32 s1, s31, s49
	s_cselect_b32 s0, s30, s48
	v_lshlrev_b64 v[64:65], 10, v[72:73]
	v_lshl_add_u64 v[64:65], s[0:1], 0, v[64:65]
	s_lshl_b32 s64, s61, 1
	v_lshl_add_u64 v[64:65], v[64:65], 0, s[64:65]
	s_lshl_b32 s64, s91, 1
	v_lshl_add_u64 v[64:65], v[64:65], 0, s[64:65]
	v_lshlrev_b32_e32 v66, 1, v142
	v_mov_b32_e32 v67, v141
	v_lshl_add_u64 v[64:65], v[64:65], 0, v[66:67]
	s_and_b64 vcc, exec, s[4:5]
	v_cvt_pk_bf16_f32 v60, v60, v61
	v_cvt_pk_bf16_f32 v61, v62, v63
	v_cvt_pk_bf16_f32 v62, v56, v57
	v_cvt_pk_bf16_f32 v63, v58, v59
	global_store_dwordx4 v[64:65], v[60:63], off
	v_cvt_pk_bf16_f32 v52, v52, v53
	v_cvt_pk_bf16_f32 v53, v54, v55
	v_cvt_pk_bf16_f32 v54, v48, v49
	s_nop 0
	v_cvt_pk_bf16_f32 v55, v50, v51
	global_store_dwordx4 v[64:65], v[52:55], off offset:256
	v_add_u32_e32 v56, 0x90, v156
	s_and_b64 vcc, exec, s[8:9]
	s_mov_b64 s[0:1], -1
	s_cbranch_vccnz .LBB0_286
	s_branch .LBB0_307
.Lbg_5:
	s_and_b64 s[0:1], s[80:81], exec
	v_ashrrev_i32_e32 v57, 31, v56
	s_cselect_b32 s1, s31, s49
	s_cselect_b32 s0, s30, s48
	v_lshlrev_b64 v[48:49], 10, v[56:57]
	v_lshl_add_u64 v[48:49], s[0:1], 0, v[48:49]
	s_lshl_b32 s64, s61, 1
	v_lshl_add_u64 v[48:49], v[48:49], 0, s[64:65]
	s_lshl_b32 s64, s91, 1
	v_lshl_add_u64 v[48:49], v[48:49], 0, s[64:65]
	v_lshlrev_b32_e32 v50, 1, v142
	v_mov_b32_e32 v51, v141
	v_lshl_add_u64 v[48:49], v[48:49], 0, v[50:51]
	s_and_b64 vcc, exec, s[4:5]
	v_cvt_pk_bf16_f32 v44, v44, v45
	v_cvt_pk_bf16_f32 v45, v46, v47
	v_cvt_pk_bf16_f32 v46, v40, v41
	v_cvt_pk_bf16_f32 v47, v42, v43
	global_store_dwordx4 v[48:49], v[44:47], off
	v_cvt_pk_bf16_f32 v36, v36, v37
	v_cvt_pk_bf16_f32 v37, v38, v39
	v_cvt_pk_bf16_f32 v38, v32, v33
	s_nop 0
	v_cvt_pk_bf16_f32 v39, v34, v35
	global_store_dwordx4 v[48:49], v[36:39], off offset:256
	v_add_u32_e32 v40, 0xa0, v156
	s_and_b64 vcc, exec, s[8:9]
	s_mov_b64 s[0:1], -1
	s_cbranch_vccnz .LBB0_288
	s_branch .LBB0_323
.Lbg_6:
	s_and_b64 s[0:1], s[80:81], exec
	v_ashrrev_i32_e32 v41, 31, v40
	s_cselect_b32 s1, s31, s49
	s_cselect_b32 s0, s30, s48
	v_lshlrev_b64 v[32:33], 10, v[40:41]
	v_lshl_add_u64 v[32:33], s[0:1], 0, v[32:33]
	s_lshl_b32 s64, s61, 1
	v_lshl_add_u64 v[32:33], v[32:33], 0, s[64:65]
	s_lshl_b32 s64, s91, 1
	v_lshl_add_u64 v[32:33], v[32:33], 0, s[64:65]
	v_lshlrev_b32_e32 v34, 1, v142
	v_mov_b32_e32 v35, v141
	v_lshl_add_u64 v[32:33], v[32:33], 0, v[34:35]
	s_and_b64 vcc, exec, s[4:5]
	v_cvt_pk_bf16_f32 v28, v28, v29
	v_cvt_pk_bf16_f32 v29, v30, v31
	v_cvt_pk_bf16_f32 v30, v24, v25
	v_cvt_pk_bf16_f32 v31, v26, v27
	global_store_dwordx4 v[32:33], v[28:31], off
	v_cvt_pk_bf16_f32 v20, v20, v21
	v_cvt_pk_bf16_f32 v21, v22, v23
	v_cvt_pk_bf16_f32 v22, v16, v17
	s_nop 0
	v_cvt_pk_bf16_f32 v23, v18, v19
	global_store_dwordx4 v[32:33], v[20:23], off offset:256
	v_add_u32_e32 v24, 0xb0, v156
	s_and_b64 vcc, exec, s[8:9]
	s_mov_b64 s[0:1], -1
	s_cbranch_vccnz .LBB0_290
	s_branch .LBB0_339
.Lbg_7:
	s_and_b64 s[0:1], s[80:81], exec
	v_ashrrev_i32_e32 v25, 31, v24
	s_cselect_b32 s1, s31, s49
	s_cselect_b32 s0, s30, s48
	v_lshlrev_b64 v[16:17], 10, v[24:25]
	v_lshl_add_u64 v[16:17], s[0:1], 0, v[16:17]
	s_lshl_b32 s64, s61, 1
	v_lshl_add_u64 v[16:17], v[16:17], 0, s[64:65]
	s_lshl_b32 s64, s91, 1
	v_lshl_add_u64 v[16:17], v[16:17], 0, s[64:65]
	v_lshlrev_b32_e32 v140, 1, v142
	v_lshl_add_u64 v[16:17], v[16:17], 0, v[140:141]
	s_and_b64 vcc, exec, s[4:5]
	v_cvt_pk_bf16_f32 v12, v12, v13
	v_cvt_pk_bf16_f32 v13, v14, v15
	v_cvt_pk_bf16_f32 v14, v8, v9
	v_cvt_pk_bf16_f32 v15, v10, v11
	global_store_dwordx4 v[16:17], v[12:15], off
	s_branch .LBB0_207
